# attention unit prologue: the full VMEM drain before staging tile 0 replaced by a counted wait (only the four K/V loads are needed there; Q keeps its own counted waits)
# baseline (speedup 1.0000x reference)
; __device__ __forceinline__ int v_st(int k, int c) { const int kk = (k & ~0xC) | ((k & 4) << 1) | ((k & 8) >> 1); return ((kk >> 3) * 4 + (c >> 5)) * 512 + ((kk & 7) * 32 + (c & 31)) * 2; }
; __device__ __forceinline__ int v_rd_base(int lane) { return ((lane & 3) << 3) | (((lane >> 2) & 3) << 6) | (((lane >> 4) & 1) << 5) | (((lane >> 5) & 1) << 8); }
; #define SLOAD(i, k0) do { sr_[i].vs0 = St::ld8(&Vh[(long)((k0) + sr) * LDK + sc]); sr_[i].vs1 = St::ld8(&Vh[(long)((k0) + 32 + sr) * LDK + sc]); \
;     sr_[i].ks0 = St::ld8(&Kh[(long)((k0) + sr) * LDK + sc]); sr_[i].ks1 = St::ld8(&Kh[(long)((k0) + 32 + sr) * LDK + sc]); } while (0)
; template <typename TQ>
; __device__ __forceinline__ void attn_dense_body(const TQ* __restrict__ Qb, const bf16* __restrict__ Kh, const bf16* __restrict__ Vh,
;                                                 unsigned short* __restrict__ Ob, int seq, char* lds) {
;     ...
;   const TQ* Qw = Qb + (long)(wid * QBLK + r32) * LDQ + hi * 8;
; #pragma unroll
;   for (int d0 = 0; d0 < 8; ++d0) qr[d0] = SQ::tobf(SQ::ld8(Qw + d0 * 16));
;   const int sr = tid >> 4, sc = (tid & 15) * 8, vst0 = v_st(sr, sc), vst1 = v_st(32 + sr, sc);
;   const int vb0 = (int)(uintptr_t)V_lds + v_rd_base(lane);
;   struct { typename St::T vs0, vs1, ks0, ks1; } sr_[SDEPTH];
;     ...
;   f32x16 pA0, pA1, pB0, pB1; float mnA, mnB, alA, alB; bf16x8 pa0, pa1, pa2, pa3; const int NT = seq / KVBLK;
;   constexpr int SE = 0, SO = SDEPTH - 1;
;   SLOAD(SE, 0); asm volatile("s_waitcnt vmcnt(0)" ::: "memory"); SWRITE(0, SE); __syncthreads();
.LBB0_1585:
	s_bfe_u32 s34, s33, 0x10007
	s_bfe_u32 s4, s33, 0x20005
	s_ashr_i32 s65, s33, 8
	s_lshl_b32 s5, s34, 2
	s_or_b32 s63, s5, s4
	s_lshl_b32 s4, s65, 3
	s_or_b32 s4, s63, s4
	s_ashr_i32 s5, s4, 31
	s_lshl_b32 s35, s33, 8
	s_and_b32 s66, s35, 0x1f00
	s_lshl_b64 s[4:5], s[4:5], 21
	s_add_u32 s4, s47, s4
	s_addc_u32 s5, s64, s5
	s_lshl_b32 s35, s66, 8
	s_add_u32 s38, s4, s35
	s_addc_u32 s39, s5, 0
	s_lshl_b32 s4, s65, 1
	s_or_b32 s5, s4, s34
	s_mul_hi_i32 s4, s5, 0x210000
	s_mul_i32 s5, s5, 0x210000
	s_add_u32 s34, s24, s5
	s_addc_u32 s35, s25, s4
	s_add_u32 s36, s26, s5
	s_addc_u32 s37, s27, s4
	global_load_dwordx4 v[2:5], v189, s[36:37]
	global_load_dwordx4 v[6:9], v190, s[36:37]
	global_load_dwordx4 v[10:13], v189, s[34:35]
	global_load_dwordx4 v[14:17], v190, s[34:35]
	v_mov_b32_e32 v177, v167
	v_lshl_add_u64 v[18:19], s[38:39], 0, v[176:177]
	v_lshl_add_u64 v[18:19], v[18:19], 0, v[178:179]
	global_load_dwordx4 v[126:129], v[18:19], off
	global_load_dwordx4 v[122:125], v[18:19], off offset:32
	global_load_dwordx4 v[118:121], v[18:19], off offset:64
	global_load_dwordx4 v[114:117], v[18:19], off offset:96
	global_load_dwordx4 v[110:113], v[18:19], off offset:128
	global_load_dwordx4 v[106:109], v[18:19], off offset:160
	global_load_dwordx4 v[102:105], v[18:19], off offset:192
	global_load_dwordx4 v[98:101], v[18:19], off offset:224
	s_waitcnt vmcnt(8)
	s_movk_i32 s67, 0x100
	s_mov_b32 s68, 1
	v_mov_b32_e32 v175, 0
	s_waitcnt vmcnt(11)
	ds_write_b128 v191, v[2:5]
	s_waitcnt vmcnt(10)
	ds_write_b128 v192, v[6:9]
	s_waitcnt vmcnt(9)
	ds_write_b128 v193, v[10:13] offset:32768
	s_waitcnt vmcnt(8)
	ds_write_b128 v194, v[14:17] offset:32768
	s_waitcnt lgkmcnt(0)
	s_barrier
; __device__ __forceinline__ void partialSM(f32x16& p0, f32x16& p1, float& m_reg, float& mn, float& alpha) {
;   constexpr float C = SCALE * 1.4426950408889634f;
;   float pmax = p0[0]; for (int r = 1; r < 16; ++r) pmax = fmaxf(pmax, p0[r]); for (int r = 0; r < 16; ++r) pmax = fmaxf(pmax, p1[r]);
;   { auto rr = __builtin_amdgcn_permlane32_swap(__float_as_uint(pmax), __float_as_uint(pmax), false, false);
;     pmax = fmaxf(__uint_as_float(rr[0]), __uint_as_float(rr[1])); }
;   if (__builtin_expect(__all(pmax - m_reg <= THR / SCALE), 1)) { mn = m_reg; alpha = 1.f; }
;   else { mn = fmaxf(m_reg, pmax); alpha = __builtin_amdgcn_exp2f((m_reg - mn) * C); m_reg = mn; }
;   float mnC = -mn * C;
;   for (int r = 0; r < 16; ++r) p0[r] = fmaf(p0[r], C, mnC); for (int r = 0; r < 16; ++r) p1[r] = fmaf(p1[r], C, mnC);
;   for (int r = 0; r < 16; ++r) p0[r] = __builtin_amdgcn_exp2f(p0[r]);
; }
; __device__ __forceinline__ void finishSM(f32x16& p0, f32x16& p1, float alpha, float& l_reg, bf16x8& pa0, bf16x8& pa1, bf16x8& pa2, bf16x8& pa3) {
;   for (int r = 0; r < 16; ++r) p1[r] = __builtin_amdgcn_exp2f(p1[r]);
;   float ps = 0; for (int r = 0; r < 16; ++r) ps += p0[r]; for (int r = 0; r < 16; ++r) ps += p1[r];
;   { auto rr = __builtin_amdgcn_permlane32_swap(__float_as_uint(ps), __float_as_uint(ps), false, false);
;     ps = __uint_as_float(rr[0]) + __uint_as_float(rr[1]); }
;   l_reg = l_reg * alpha + ps;
;     ...
;   PK4(p0, 0, pa0); PK4(p0, 8, pa1); PK4(p1, 0, pa2); PK4(p1, 8, pa3);
;     ...
; }
; __device__ __forceinline__ void qkt(f32x16& p0, f32x16& p1, const bf16* Ks, const bf16x8* qr, int r32, int hi) {
;   p0 = f32x16{}; p1 = f32x16{};
;   for (int d0 = 0; d0 < 8; ++d0) { int cb = (d0 * 16 + hi * 8) * 2;
;     bf16x8 b0 = *reinterpret_cast<const bf16x8*>((const char*)Ks + KSWZ(r32, cb));
;     bf16x8 b1 = *reinterpret_cast<const bf16x8*>((const char*)Ks + KSWZ(32 + r32, cb));
;     p0 = __builtin_amdgcn_mfma_f32_32x32x16_bf16(b0, qr[d0], p0, 0, 0, 0);
;     p1 = __builtin_amdgcn_mfma_f32_32x32x16_bf16(b1, qr[d0], p1, 0, 0, 0); }
	ds_read_b128 v[2:5], v195 offset:32768
	ds_read_b128 v[6:9], v195 offset:40960
	s_waitcnt vmcnt(7) lgkmcnt(1)
	v_mfma_f32_32x32x16_bf16 v[34:49], v[2:5], v[126:129], 0
	s_waitcnt lgkmcnt(0)
	v_mfma_f32_32x32x16_bf16 v[50:65], v[6:9], v[126:129], 0
	ds_read_b128 v[2:5], v196 offset:32768
	ds_read_b128 v[6:9], v196 offset:40960
	s_waitcnt vmcnt(6) lgkmcnt(1)
	v_mfma_f32_32x32x16_bf16 v[34:49], v[2:5], v[122:125], v[34:49]
	s_waitcnt lgkmcnt(0)
	v_mfma_f32_32x32x16_bf16 v[50:65], v[6:9], v[122:125], v[50:65]
	ds_read_b128 v[2:5], v197 offset:32768
	ds_read_b128 v[6:9], v197 offset:40960
	s_waitcnt vmcnt(5) lgkmcnt(1)
	v_mfma_f32_32x32x16_bf16 v[34:49], v[2:5], v[118:121], v[34:49]
	s_waitcnt lgkmcnt(0)
	v_mfma_f32_32x32x16_bf16 v[50:65], v[6:9], v[118:121], v[50:65]
	ds_read_b128 v[2:5], v198 offset:32768
	ds_read_b128 v[6:9], v198 offset:40960
	s_waitcnt vmcnt(4) lgkmcnt(1)
	v_mfma_f32_32x32x16_bf16 v[34:49], v[2:5], v[114:117], v[34:49]
	s_waitcnt lgkmcnt(0)
	v_mfma_f32_32x32x16_bf16 v[50:65], v[6:9], v[114:117], v[50:65]
	ds_read_b128 v[2:5], v199 offset:32768
	ds_read_b128 v[6:9], v199 offset:40960
	s_waitcnt vmcnt(3) lgkmcnt(1)
	v_mfma_f32_32x32x16_bf16 v[34:49], v[2:5], v[110:113], v[34:49]
	s_waitcnt lgkmcnt(0)
	v_mfma_f32_32x32x16_bf16 v[50:65], v[6:9], v[110:113], v[50:65]
	ds_read_b128 v[2:5], v200 offset:32768
	ds_read_b128 v[6:9], v200 offset:40960
	s_waitcnt vmcnt(2) lgkmcnt(1)
	v_mfma_f32_32x32x16_bf16 v[34:49], v[2:5], v[106:109], v[34:49]
	s_waitcnt lgkmcnt(0)
	v_mfma_f32_32x32x16_bf16 v[50:65], v[6:9], v[106:109], v[50:65]
	ds_read_b128 v[2:5], v201 offset:32768
	ds_read_b128 v[6:9], v201 offset:40960
	global_load_dwordx4 v[66:69], v205, s[36:37]
	global_load_dwordx4 v[70:73], v204, s[36:37]
	global_load_dwordx4 v[74:77], v204, s[34:35]
	global_load_dwordx4 v[78:81], v205, s[34:35]
	ds_read_b128 v[18:21], v202 offset:32768
	ds_read_b128 v[82:85], v202 offset:40960
	global_load_dwordx4 v[130:133], v206, s[36:37]
	global_load_dwordx4 v[134:137], v206, s[34:35]
	global_load_dwordx4 v[142:145], v207, s[36:37]
	global_load_dwordx4 v[138:141], v207, s[34:35]
	s_waitcnt vmcnt(4)
	s_waitcnt vmcnt(9) lgkmcnt(3)
	v_mfma_f32_32x32x16_bf16 v[34:49], v[2:5], v[102:105], v[34:49]
	s_waitcnt vmcnt(6)
	ds_write_b128 v191, v[70:73] offset:16384
	ds_write_b128 v192, v[66:69] offset:16384
	s_waitcnt vmcnt(5)
	ds_write_b128 v193, v[74:77] offset:49152
	s_waitcnt vmcnt(4)
	ds_write_b128 v194, v[78:81] offset:49152
	s_waitcnt lgkmcnt(6)
	v_mfma_f32_32x32x16_bf16 v[50:65], v[6:9], v[102:105], v[50:65]
	v_mov_b64_e32 v[2:3], s[8:9]
	v_mov_b64_e32 v[16:17], s[22:23]
	v_mov_b64_e32 v[4:5], s[10:11]
	v_mov_b64_e32 v[6:7], s[12:13]
	v_mov_b64_e32 v[8:9], s[14:15]
	v_mov_b64_e32 v[10:11], s[16:17]
	v_mov_b64_e32 v[12:13], s[18:19]
	s_waitcnt lgkmcnt(5)
	v_mfma_f32_32x32x16_bf16 v[34:49], v[18:21], v[98:101], v[34:49]
	v_mov_b64_e32 v[14:15], s[20:21]
	v_mov_b64_e32 v[32:33], v[16:17]
	v_mov_b64_e32 v[30:31], v[14:15]
	v_mov_b64_e32 v[28:29], v[12:13]
	v_mov_b64_e32 v[26:27], v[10:11]
	v_mov_b64_e32 v[24:25], v[8:9]
	v_mov_b64_e32 v[22:23], v[6:7]
	s_waitcnt lgkmcnt(4)
	v_mfma_f32_32x32x16_bf16 v[50:65], v[82:85], v[98:101], v[50:65]
	s_nop 2
	v_max_f32_e32 v82, v35, v35
	v_max_f32_e32 v83, v34, v34
	v_max_f32_e32 v82, v83, v82
	v_max3_f32 v82, v82, v36, v37
	v_max3_f32 v82, v82, v38, v39
	v_max3_f32 v82, v82, v40, v41
	v_max3_f32 v82, v82, v42, v43
	v_max3_f32 v82, v82, v44, v45
	v_max3_f32 v82, v82, v46, v47
	v_max3_f32 v66, v82, v48, v49
	v_max3_f32 v66, v66, v50, v51
	v_max3_f32 v66, v66, v52, v53
	v_max3_f32 v66, v66, v54, v55
	v_max3_f32 v66, v66, v56, v57
	v_max3_f32 v66, v66, v58, v59
	v_max3_f32 v66, v66, v60, v61
	v_max3_f32 v66, v66, v62, v63
	v_max3_f32 v66, v66, v64, v65
	v_mov_b32_e32 v67, v66
	s_nop 1
	v_permlane32_swap_b32_e32 v66, v67
	v_max_f32_e32 v67, v67, v67
	v_max_f32_e32 v66, v66, v66
	v_max_f32_e32 v66, v66, v67
	v_add_f32_e32 v67, 0x7149f2ca, v66
	v_cmp_ge_f32_e32 vcc, s48, v67
	s_cmp_eq_u64 vcc, exec
	v_max_f32_e32 v66, 0xf149f2ca, v66
	s_cselect_b64 vcc, -1, 0
	v_sub_f32_e32 v67, 0xf149f2ca, v66
	v_cndmask_b32_e32 v208, v66, v203, vcc
	v_mul_f32_e32 v67, 0x3e0293ee, v67
	v_mul_f32_e32 v66, 0xbe0293ee, v208
	v_exp_f32_e32 v67, v67
	v_mov_b32_e32 v68, v66
	v_fmamk_f32 v34, v34, 0x3e0293ee, v66
	v_fmamk_f32 v35, v35, 0x3e0293ee, v66
	v_fmamk_f32 v36, v36, 0x3e0293ee, v66
	v_fmamk_f32 v37, v37, 0x3e0293ee, v66
	v_fmamk_f32 v38, v38, 0x3e0293ee, v66
	v_fmamk_f32 v39, v39, 0x3e0293ee, v66
	v_fmamk_f32 v40, v40, 0x3e0293ee, v66
	v_fmamk_f32 v41, v41, 0x3e0293ee, v66
	v_fmamk_f32 v42, v42, 0x3e0293ee, v66
	v_fmamk_f32 v43, v43, 0x3e0293ee, v66
	v_fmamk_f32 v44, v44, 0x3e0293ee, v66
	v_fmamk_f32 v45, v45, 0x3e0293ee, v66
	v_fmamk_f32 v46, v46, 0x3e0293ee, v66
	v_fmamk_f32 v47, v47, 0x3e0293ee, v66
	v_fmamk_f32 v48, v48, 0x3e0293ee, v66
	v_fmac_f32_e32 v68, 0x3e0293ee, v49
	v_exp_f32_e32 v224, v34
	v_exp_f32_e32 v226, v35
	v_exp_f32_e32 v222, v36
	v_exp_f32_e32 v225, v37
	v_exp_f32_e32 v164, v38
	v_exp_f32_e32 v223, v39
	v_exp_f32_e32 v220, v40
	v_exp_f32_e32 v221, v41
	v_exp_f32_e32 v217, v42
	v_exp_f32_e32 v219, v43
	v_exp_f32_e32 v216, v44
	v_exp_f32_e32 v218, v45
	v_exp_f32_e32 v213, v46
	v_exp_f32_e32 v215, v47
	v_exp_f32_e32 v212, v48
	v_exp_f32_e32 v214, v68
	s_add_u32 s38, s90, s5
	v_pk_fma_f32 v[152:153], v[64:65], s[30:31], v[66:67] op_sel_hi:[1,0,0]
	v_pk_fma_f32 v[158:159], v[62:63], s[30:31], v[66:67] op_sel_hi:[1,0,0]
	v_pk_fma_f32 v[160:161], v[60:61], s[30:31], v[66:67] op_sel_hi:[1,0,0]
	v_pk_fma_f32 v[146:147], v[58:59], s[30:31], v[66:67] op_sel_hi:[1,0,0]
	v_pk_fma_f32 v[148:149], v[56:57], s[30:31], v[66:67] op_sel_hi:[1,0,0]
	v_pk_fma_f32 v[150:151], v[54:55], s[30:31], v[66:67] op_sel_hi:[1,0,0]
	v_pk_fma_f32 v[154:155], v[52:53], s[30:31], v[66:67] op_sel_hi:[1,0,0]
	v_pk_fma_f32 v[156:157], v[50:51], s[30:31], v[66:67] op_sel_hi:[1,0,0]
	v_mov_b64_e32 v[64:65], v[16:17]
	v_mov_b64_e32 v[48:49], v[16:17]
	v_mov_b64_e32 v[20:21], v[4:5]
	v_mov_b64_e32 v[18:19], v[2:3]
	s_addc_u32 s39, s91, s4
	v_cndmask_b32_e64 v177, v67, 1.0, vcc
	v_mov_b64_e32 v[62:63], v[14:15]
	v_mov_b64_e32 v[60:61], v[12:13]
	v_mov_b64_e32 v[58:59], v[10:11]
	v_mov_b64_e32 v[56:57], v[8:9]
	v_mov_b64_e32 v[54:55], v[6:7]
	v_mov_b64_e32 v[52:53], v[4:5]
	v_mov_b64_e32 v[50:51], v[2:3]
	v_mov_b64_e32 v[46:47], v[14:15]
	v_mov_b64_e32 v[44:45], v[12:13]
	v_mov_b64_e32 v[42:43], v[10:11]
	v_mov_b64_e32 v[40:41], v[8:9]
	v_mov_b64_e32 v[38:39], v[6:7]
	v_mov_b64_e32 v[36:37], v[4:5]
	v_mov_b64_e32 v[34:35], v[2:3]
	s_waitcnt lgkmcnt(0)
	s_barrier
